# global barriers, top level: waiting XCD leaders poll the top arrive counter (>= target) instead of the generation word
# baseline (speedup 1.0000x reference)
.LBB0_44:
	s_or_b64 exec, exec, s[6:7]
	v_cvt_f32_u32_e32 v5, v2
	s_waitcnt vmcnt(0)
	v_readfirstlane_b32 s4, v4
	s_mov_b64 s[6:7], -1
	v_rcp_iflag_f32_e32 v5, v5
	v_add_u32_e32 v3, s4, v3
	v_add_u32_e32 v6, 1, v3
	v_readlane_b32 s4, v253, 12
	v_mul_f32_e32 v4, 0x4f7ffffe, v5
	v_cvt_u32_f32_e32 v4, v4
	v_sub_u32_e32 v5, 0, v2
	v_readlane_b32 s5, v253, 13
	v_mul_lo_u32 v5, v5, v4
	v_mul_hi_u32 v5, v4, v5
	v_add_u32_e32 v4, v4, v5
	v_mul_hi_u32 v4, v3, v4
	v_mul_lo_u32 v5, v4, v2
	v_sub_u32_e32 v3, v3, v5
	v_add_u32_e32 v7, 1, v4
	v_cmp_ge_u32_e32 vcc, v3, v2
	v_sub_u32_e32 v5, v3, v2
	s_nop 0
	v_cndmask_b32_e32 v4, v4, v7, vcc
	v_cndmask_b32_e32 v3, v3, v5, vcc
	v_add_u32_e32 v5, 1, v4
	v_cmp_ge_u32_e32 vcc, v3, v2
	s_nop 1
	v_cndmask_b32_e32 v4, v4, v5, vcc
	v_mul_lo_u32 v3, v2, v4
	v_add_u32_e32 v2, v3, v2
	v_cmp_ne_u32_e32 vcc, v6, v2
	v_mov_b32_e32 v8, v2
	v_mov_b64_e32 v[2:3], s[4:5]
	s_and_saveexec_b64 s[4:5], vcc
	s_cbranch_execz .LBB0_56
	v_readlane_b32 s10, v253, 10
	v_readlane_b32 s11, v253, 11
	s_nop 4
.Ltop_poll:
	global_load_dword v2, v131, s[10:11] sc1
	s_waitcnt vmcnt(0)
	v_cmp_lt_u32_e32 vcc, v2, v8
	s_cbranch_vccz .Ltop_done
	s_sleep 1
	s_branch .Ltop_poll
.Ltop_done:
	s_mov_b64 s[6:7], 0
	s_branch .LBB0_56
	s_mov_b32 s13, 1
	s_branch .LBB0_48
